# v67 + code placement: scan phases (SCAN_A..SCAN_C) shifted by 4 bytes (s_nop 0 at SCAN_A entry, another at HG_WO entry)
# speedup vs baseline: 1.0052x; 1.0052x over previous
.LBB0_1095:
	s_nop 0
	s_cmp_lt_i32 s58, 12
	s_waitcnt lgkmcnt(0)
	s_cselect_b64 s[36:37], -1, 0
	s_and_b64 s[4:5], s[36:37], s[4:5]
	s_and_b64 vcc, exec, s[4:5]
	s_mov_b64 s[0:1], s[4:5]
	s_cbranch_vccnz .LBB0_1098
	s_cmp_lt_i32 s58, 13
	s_cselect_b64 s[0:1], -1, 0
	s_cmp_gt_i32 s59, 12
	s_cselect_b64 s[2:3], -1, 0
	s_and_b64 s[0:1], s[0:1], s[2:3]
	s_andn2_b64 vcc, exec, s[0:1]
	s_cbranch_vccz .LBB0_1098
	s_cmp_lt_i32 s58, 14
	s_cselect_b64 s[0:1], -1, 0
	s_cmp_gt_i32 s59, 13
	s_cselect_b64 s[2:3], -1, 0
	s_and_b64 s[0:1], s[0:1], s[2:3]

.LBB0_1400:
	s_nop 0
	s_add_u32 s2, s56, 0x4500000
	s_addc_u32 s3, s57, 0
	v_writelane_b32 v249, s2, 32
	s_cmp_lt_i32 s58, 15
	s_nop 0
	v_writelane_b32 v249, s3, 33
	s_cselect_b64 s[2:3], -1, 0
	s_and_b64 s[0:1], s[2:3], s[0:1]
	s_andn2_b64 vcc, exec, s[0:1]
	s_cbranch_vccnz .LBB0_1455
	s_and_b32 s3, s94, 1
	s_add_u32 s35, s56, 0xd500000
	s_addc_u32 s64, s57, 0
	s_add_u32 s65, s56, 0x100000
	s_addc_u32 s68, s57, 0
	s_add_u32 s69, s56, 0xca000
	s_addc_u32 s26, s57, 0
	v_readlane_b32 s0, v249, 2
	s_cmpk_lg_i32 s0, 0x100
	v_readlane_b32 s1, v249, 3
	s_cselect_b64 s[46:47], -1, 0
	s_cmpk_lt_i32 s94, 0x140
	s_mov_b32 s8, s0
	s_cselect_b64 s[0:1], -1, 0
	s_ashr_i32 s27, s94, 31
	s_lshr_b32 s2, s27, 29
	s_add_i32 s2, s94, s2
	s_ashr_i32 s4, s2, 3
	s_and_b32 s2, s2, -8
	s_sub_i32 s5, s94, s2
	s_cmp_eq_u32 s3, 0
	v_writelane_b32 v249, s0, 36
	s_cselect_b64 s[24:25], -1, 0
	s_cmp_eq_u32 s3, 1
	v_writelane_b32 v249, s1, 37
	s_cselect_b64 s[0:1], -1, 0
	s_ashr_i32 s30, s94, 2
	v_writelane_b32 v249, s0, 38
	s_add_i32 s2, s30, 0x100
	s_ashr_i32 s6, s2, 31
	v_writelane_b32 v249, s1, 39
	s_and_b32 s0, s94, 3
	s_lshr_b32 s6, s6, 29
	v_writelane_b32 v249, s0, 40
	s_lshl_b32 s11, s0, 9
	s_and_b32 s0, s94, 2
	s_add_i32 s6, s2, s6
	v_writelane_b32 v249, s0, 41
	s_ashr_i32 s10, s6, 3
	s_and_b32 s6, s6, -8
	s_ashr_i32 s7, s8, 31
	s_lshl_b32 s8, s0, 9
	v_readlane_b32 s28, v249, 32
	v_readlane_b32 s0, v249, 26
	s_sub_i32 s6, s2, s6
	v_readlane_b32 s29, v249, 33
	s_lshl_b32 s2, s0, 14
	s_and_b32 s9, s29, 0xffff
	s_and_b32 s21, s55, 0xffff
	s_add_i32 s2, s2, 0
	s_cmpk_lt_i32 s34, 0x1000
	s_cselect_b64 s[0:1], -1, 0
	s_add_i32 s16, s34, 0xfffff800
	s_add_u32 s38, s56, 0x3d00000
	s_addc_u32 s39, s57, 0
	s_add_u32 s40, s56, 0x3500000
	s_addc_u32 s41, s57, 0
	s_cmp_lt_i32 s5, 0
	s_cselect_b32 s12, 41, 40
	s_mul_i32 s5, s5, s12
	s_add_i32 s4, s5, s4
	s_ashr_i32 s5, s4, 31
	s_lshr_b32 s5, s5, 27
	s_add_i32 s5, s4, s5
	s_ashr_i32 s5, s5, 5
	s_lshl_b32 s12, s5, 5
	s_sub_i32 s12, s4, s12
	s_bfe_i32 s4, s12, 0x80000
	s_bfe_u32 s4, s4, 0x3000c
	s_lshl_b32 s13, s5, 3
	s_add_i32 s5, s12, s4
	s_bfe_i32 s4, s5, 0x80000
	s_and_b32 s5, s5, 0xf8
	v_writelane_b32 v249, s0, 42
	s_sext_i32_i16 s14, s4
	s_sub_i32 s5, s12, s5
	v_writelane_b32 v249, s1, 43
	s_ashr_i32 s0, s14, 3
	s_sext_i32_i8 s5, s5
	v_writelane_b32 v249, s0, 44
	s_add_i32 s0, s13, s5
	s_lshr_b32 s4, s14, 3
	s_lshl_b32 s14, s0, 8
	s_ashr_i32 s15, s14, 31
	v_writelane_b32 v249, s0, 45
	s_lshl_b64 s[0:1], s[14:15], 11
	v_writelane_b32 v249, s0, 46
	s_bfe_i64 s[4:5], s[4:5], 0x100000
	v_lshrrev_b32_e32 v1, 1, v0
	v_writelane_b32 v249, s1, 47
	s_lshl_b64 s[0:1], s[4:5], 19
	s_cmp_lt_i32 s6, 0
	s_cselect_b32 s4, 41, 40
	s_mul_i32 s4, s6, s4
	s_add_i32 s4, s4, s10
	s_ashr_i32 s5, s4, 31
	s_lshr_b32 s5, s5, 27
	s_add_i32 s5, s4, s5
	s_ashr_i32 s6, s5, 5
	s_lshl_b32 s33, s6, 3
	s_andn2_b32 s5, s5, 31
	s_sub_i32 s6, 0x50, s33
	s_sub_i32 s15, s4, s5
	s_sub_i32 s4, 0x50, s13
	s_min_i32 s14, s6, 8
	s_min_i32 s17, s4, 8
	v_writelane_b32 v249, s0, 48
	s_cmpk_lt_i32 s34, 0x800
	s_movk_i32 s4, 0x400
	s_mov_b32 s5, 0x3500000
	v_writelane_b32 v249, s1, 49
	s_cselect_b32 s0, s4, 0x1000
	s_cselect_b32 s5, s5, 0x3d00000
	v_writelane_b32 v249, s0, 50
	s_cselect_b32 s10, s77, s79
	s_cselect_b32 s18, s76, s78
	s_cselect_b32 s0, 0x1000, s4
	s_cselect_b32 s29, s34, s16
	s_cselect_b32 s6, 12, 10
	s_add_u32 s4, s56, s5
	s_addc_u32 s5, s57, 0
	v_writelane_b32 v249, s4, 51
	v_lshrrev_b32_e32 v3, 5, v0
	v_and_b32_e32 v1, 24, v1
	v_writelane_b32 v249, s5, 52
	s_add_u32 s4, s18, 0x1000000
	v_and_b32_e32 v3, 4, v3
	v_bfe_u32 v4, v0, 2, 2
	s_addc_u32 s5, s10, 0
	s_abs_i32 s16, s14
	v_or3_b32 v3, v3, v4, v1
	v_cvt_f32_u32_e32 v4, s16
	s_sub_i32 s20, 0, s16
	s_abs_i32 s19, s15
	v_bfe_u32 v1, v0, 3, 25
	v_rcp_iflag_f32_e32 v4, v4
	v_bfe_u32 v2, v0, 2, 4
	v_or_b32_e32 v1, 64, v1
	s_movk_i32 s10, 0x70
	v_mul_f32_e32 v4, 0x4f7ffffe, v4
	v_cvt_u32_f32_e32 v4, v4
	v_and_or_b32 v5, v1, s10, v2
	s_movk_i32 s10, 0x60
	s_xor_b32 s18, s15, s14
	v_readfirstlane_b32 s22, v4
	s_mul_i32 s20, s20, s22
	s_mul_hi_u32 s20, s22, s20
	s_add_i32 s22, s22, s20
	s_mul_hi_u32 s20, s19, s22
	s_mul_i32 s22, s20, s16
	s_sub_i32 s19, s19, s22
	v_and_or_b32 v1, v1, s10, v3
	s_lshr_b32 s10, s0, 5
	s_ashr_i32 s18, s18, 31
	s_add_i32 s22, s20, 1
	s_sub_i32 s23, s19, s16
	s_cmp_ge_u32 s19, s16
	s_cselect_b32 s20, s22, s20
	s_cselect_b32 s19, s23, s19
	s_add_i32 s22, s20, 1
	s_cmp_ge_u32 s19, s16
	s_movk_i32 s16, 0x200
	v_lshlrev_b32_e32 v4, 11, v5
	v_or_b32_e32 v5, 0xfffc0000, v4
	v_cmp_gt_u32_e32 vcc, s16, v0
	s_cselect_b32 s16, s22, s20
	s_abs_i32 s19, s17
	v_cndmask_b32_e32 v21, v5, v4, vcc
	v_cvt_f32_u32_e32 v4, s19
	v_lshlrev_b32_e32 v1, 11, v1
	v_or_b32_e32 v5, 0xfffc0000, v1
	v_cndmask_b32_e32 v23, v5, v1, vcc
	v_rcp_iflag_f32_e32 v1, v4
	s_xor_b32 s16, s16, s18
	v_writelane_b32 v249, s0, 53
	s_sub_i32 s0, s16, s18
	v_mul_f32_e32 v1, 0x4f7ffffe, v1
	v_cvt_u32_f32_e32 v1, v1
	s_mul_i32 s14, s0, s14
	s_sub_i32 s14, s15, s14
	s_sub_i32 s15, 0, s19
	v_readfirstlane_b32 s16, v1
	s_mul_i32 s15, s15, s16
	s_mul_hi_u32 s15, s16, s15
	s_add_i32 s1, s33, s14
	s_abs_i32 s14, s12
	s_add_i32 s16, s16, s15
	s_mul_hi_u32 s16, s14, s16
	s_mul_i32 s15, s16, s19
	s_sub_i32 s18, s14, s15
	s_lshl_b32 s14, s1, 8
	v_writelane_b32 v249, s1, 26
	s_ashr_i32 s15, s14, 31
	s_ashr_i32 s1, s0, 31
	s_lshl_b64 s[36:37], s[14:15], 11
	s_xor_b32 s14, s12, s17
	s_lshl_b64 s[44:45], s[0:1], 19
	s_ashr_i32 s14, s14, 31
	s_or_b32 s42, s36, s11
	s_mov_b32 s1, s30
	s_or_b32 s30, s44, s11
	s_add_i32 s11, s16, 1
	s_sub_i32 s15, s18, s19
	s_cmp_ge_u32 s18, s19
	s_cselect_b32 s11, s11, s16
	s_cselect_b32 s15, s15, s18
	s_add_i32 s16, s11, 1
	s_cmp_ge_u32 s15, s19
	s_cselect_b32 s11, s16, s11
	s_or_b32 s36, s36, s8
	s_or_b32 s44, s44, s8
	s_abs_i32 s8, s10
	v_cvt_f32_u32_e32 v1, s8
	s_xor_b32 s11, s11, s14
	s_sub_i32 s70, s11, s14
	s_mul_i32 s11, s70, s17
	v_rcp_iflag_f32_e32 v1, v1
	s_sub_i32 s11, s12, s11
	s_add_i32 s33, s13, s11
	s_sub_i32 s11, 0, s8
	v_mul_f32_e32 v1, 0x4f7ffffe, v1
	v_cvt_u32_f32_e32 v1, v1
	s_ashr_i32 s71, s70, 31
	s_lshl_b64 s[16:17], s[70:71], 19
	v_lshlrev_b32_e32 v22, 3, v0
	v_readfirstlane_b32 s12, v1
	s_mul_i32 s11, s11, s12
	s_mul_hi_u32 s11, s12, s11
	s_add_i32 s12, s12, s11
	s_abs_i32 s11, s29
	s_mul_hi_u32 s14, s11, s12
	s_mul_i32 s12, s14, s8
	s_sub_i32 s11, s11, s12
	s_lshl_b32 s12, s33, 8
	s_ashr_i32 s13, s12, 31
	s_lshl_b64 s[12:13], s[12:13], 11
	v_writelane_b32 v249, s12, 34
	s_sub_i32 s15, s11, s8
	v_lshrrev_b32_e32 v1, 3, v204
	v_writelane_b32 v249, s13, 35
	s_xor_b32 s12, s29, s10
	s_ashr_i32 s12, s12, 31
	s_add_i32 s13, s14, 1
	s_cmp_ge_u32 s11, s8
	s_cselect_b32 s13, s13, s14
	s_cselect_b32 s11, s15, s11
	s_add_i32 s14, s13, 1
	s_cmp_ge_u32 s11, s8
	s_cselect_b32 s8, s14, s13
	s_xor_b32 s8, s8, s12
	s_sub_i32 s8, s8, s12
	v_lshl_or_b32 v4, s8, 6, v1
	v_writelane_b32 v249, s16, 54
	v_ashrrev_i32_e32 v5, 31, v4
	v_lshlrev_b64 v[6:7], s6, v[4:5]
	v_writelane_b32 v249, s17, 55
	v_or_b32_e32 v8, 8, v4
	v_or_b32_e32 v10, 16, v4
	v_or_b32_e32 v12, 24, v4
	v_or_b32_e32 v14, 32, v4
	v_or_b32_e32 v16, 40, v4
	v_or_b32_e32 v18, 48, v4
	v_or_b32_e32 v4, 56, v4
	v_lshlrev_b32_e32 v24, 2, v0
	v_and_b32_e32 v22, 56, v22
	v_ashrrev_i32_e32 v9, 31, v8
	v_ashrrev_i32_e32 v11, 31, v10
	v_ashrrev_i32_e32 v13, 31, v12
	v_ashrrev_i32_e32 v15, 31, v14
	v_ashrrev_i32_e32 v17, 31, v16
	v_ashrrev_i32_e32 v19, 31, v18
	v_ashrrev_i32_e32 v5, 31, v4
	v_writelane_b32 v249, s29, 56
	v_and_b32_e32 v20, 28, v24
	v_mul_u32_u24_e32 v26, 0x84, v22
	v_lshlrev_b32_e32 v27, 2, v1
	v_lshlrev_b64 v[8:9], s6, v[8:9]
	v_lshlrev_b64 v[10:11], s6, v[10:11]
	v_lshlrev_b64 v[12:13], s6, v[12:13]
	v_lshlrev_b64 v[14:15], s6, v[14:15]
	v_lshlrev_b64 v[16:17], s6, v[16:17]
	v_lshlrev_b64 v[18:19], s6, v[18:19]
	v_lshlrev_b64 v[4:5], s6, v[4:5]
	s_mul_i32 s8, s8, s10
	v_lshlrev_b32_e32 v170, 2, v20
	v_add3_u32 v205, s2, v26, v27
	v_lshlrev_b32_e32 v26, 4, v0
	v_and_b32_e32 v27, 32, v0
	v_writelane_b32 v249, s36, 57
	v_lshl_add_u64 v[6:7], v[6:7], 2, s[4:5]
	v_lshl_add_u64 v[8:9], v[8:9], 2, s[4:5]
	v_lshl_add_u64 v[10:11], v[10:11], 2, s[4:5]
	v_lshl_add_u64 v[12:13], v[12:13], 2, s[4:5]
	v_lshl_add_u64 v[14:15], v[14:15], 2, s[4:5]
	v_lshl_add_u64 v[16:17], v[16:17], 2, s[4:5]
	v_lshl_add_u64 v[18:19], v[18:19], 2, s[4:5]
	v_lshl_add_u64 v[4:5], v[4:5], 2, s[4:5]
	s_sub_i32 s4, s29, s8
	v_add_u32_e32 v25, s2, v170
	v_bitop3_b32 v26, v26, v27, 48 bitop3:0x6c
	v_lshlrev_b32_e32 v27, 8, v0
	s_mov_b32 s2, 0x18000
	v_and_b32_e32 v28, 64, v0
	v_lshrrev_b32_e32 v29, 3, v0
	v_writelane_b32 v249, s37, 58
	s_mov_b32 s43, s37
	s_lshl_b32 s4, s4, 5
	v_and_or_b32 v27, v27, s2, v26
	v_or_b32_e32 v26, v26, v28
	v_and_or_b32 v3, v29, 32, v3
	v_writelane_b32 v249, s42, 59
	s_ashr_i32 s5, s4, 31
	v_lshl_or_b32 v174, v3, 11, v26
	v_bfe_u32 v207, v0, 4, 2
	v_lshlrev_b32_e32 v3, 6, v0
	v_writelane_b32 v249, s43, 60
	s_lshl_b64 s[4:5], s[4:5], 2
	v_or_b32_e32 v176, v21, v26
	v_lshlrev_b32_e32 v208, 4, v207
	v_and_b32_e32 v3, 0x3c0, v3
	v_and_b32_e32 v21, 32, v24
	v_writelane_b32 v249, s44, 61
	v_lshl_add_u64 v[6:7], v[6:7], 0, s[4:5]
	v_lshl_add_u64 v[8:9], v[8:9], 0, s[4:5]
	v_lshl_add_u64 v[10:11], v[10:11], 0, s[4:5]
	v_lshl_add_u64 v[12:13], v[12:13], 0, s[4:5]
	v_lshl_add_u64 v[14:15], v[14:15], 0, s[4:5]
	v_lshl_add_u64 v[16:17], v[16:17], 0, s[4:5]
	v_lshl_add_u64 v[18:19], v[18:19], 0, s[4:5]
	v_lshl_add_u64 v[4:5], v[4:5], 0, s[4:5]
	v_and_or_b32 v30, v29, 48, v2
	v_bitop3_b32 v209, v208, v21, v3 bitop3:0x36
	v_mov_b32_e32 v171, 0
	v_mul_u32_u24_e32 v3, 0x84, v1
	v_writelane_b32 v249, s45, 62
	s_mov_b32 s31, s45
	v_lshlrev_b32_e32 v2, 11, v2
	v_lshl_or_b32 v172, v30, 11, v26
	v_or_b32_e32 v178, v23, v26
	v_and_b32_e32 v206, 15, v0
	v_mov_b32_e32 v175, v171
	v_mov_b32_e32 v179, v171
	v_mov_b32_e32 v173, v171
	v_mov_b32_e32 v177, v171
	s_mov_b32 s23, 0x20000
	s_brev_b32 s22, -2
	s_mov_b32 s8, s28
	s_mov_b32 s20, s54
	v_or_b32_e32 v210, 8, v1
	v_or_b32_e32 v211, 16, v1
	v_or_b32_e32 v212, 24, v1
	v_writelane_b32 v249, s30, 63
	v_lshl_add_u64 v[180:181], v[6:7], 0, v[170:171]
	v_lshl_add_u64 v[182:183], v[8:9], 0, v[170:171]
	v_writelane_b32 v248, s31, 0
	v_lshl_add_u64 v[184:185], v[10:11], 0, v[170:171]
	v_lshl_add_u64 v[186:187], v[12:13], 0, v[170:171]
	v_lshl_add_u64 v[188:189], v[14:15], 0, v[170:171]
	v_lshl_add_u64 v[190:191], v[16:17], 0, v[170:171]
	v_lshl_add_u64 v[192:193], v[18:19], 0, v[170:171]
	v_lshl_add_u64 v[194:195], v[4:5], 0, v[170:171]
	v_or3_b32 v196, v27, v2, v28
	v_mov_b32_e32 v197, v171
	v_lshlrev_b32_e32 v170, 2, v20
	v_add_u32_e32 v213, v25, v3
	v_lshlrev_b32_e32 v198, 1, v22
	v_mov_b64_e32 v[200:201], 0x13f
	s_mov_b32 s2, 0
	s_add_i32 s4, s34, s93
	s_mov_b32 s71, 0xffff0000
	s_movk_i32 s45, 0x7fff
	s_mov_b64 s[78:79], -1
	s_mov_b64 s[76:77], 0x80
	v_writelane_b32 v248, s4, 1
	s_branch .LBB0_1404
